# v15_filter
# speedup vs baseline: 1.0072x; 1.0027x over previous
; #define LAS __attribute__((address_space(3)))
; __device__ __forceinline__ u16 f2bf(float f) { unsigned u = __float_as_uint(f); u += 0x7FFFu + ((u >> 16) & 1u); return (u16)(u >> 16); }
; __device__ __forceinline__ void phase_filter(const Params& p, int l, LAS unsigned char* lds, int bid, int G, int tid) {
;     ...
;         for (int ct = 0; ct < 4; ++ct) {
; #pragma unroll
;             for (int pt = 0; pt < 2; ++pt) {
;                 f32x16 acc;
; #pragma unroll
;                 for (int v = 0; v < 16; ++v) acc[v] = 0.f;
; #pragma unroll
;                 for (int ks = 0; ks < 4; ++ks) { const bf16x8 af = *(const LAS bf16x8*)(WT + (ct * 32 + l31) * 72 + ks * 16 + lh * 8), bf = *(const LAS bf16x8*)(H2b + (pt * 32 + l31) * 72 + ks * 16 + lh * 8);
;                     acc = __builtin_amdgcn_mfma_f32_32x32x16_bf16(af, bf, acc, 0, 0, 0); }
;                 const int pos = pb * 64 + pt * 32 + l31; const float tt = (float)pos / (float)(L - 1);
; #pragma unroll
;                 for (int v = 0; v < 16; ++v) {
;                     const int ch = slab * 128 + ct * 32 + 8 * (v >> 2) + 4 * lh + (v & 3), cc = ch & 511;
;                     const float delta = fabsf(min_d + (max_d - min_d) * ((float)cc / 511.0f));
;                     float val = (acc[v] + b3[ch]) * __expf(-tt * delta);
;                     u16* kE = kbase + (size_t)cc * pitch; u16* kO = kE + (size_t)512 * pitch;
;                     if (ch < 512) { if (pos == 0) val += hd[cc]; const u16 b = f2bf(val); kE[8 + L - pos] = b; kO[9 + L - pos] = b;
.LBB0_450:
	ds_read_b128 v[30:33], v154
	ds_read_b128 v[22:25], v154 offset:32
	ds_read_b128 v[2:5], v153
	ds_read_b128 v[18:21], v153 offset:32
	v_lshl_add_u64 v[64:65], s[94:95], 0, v[34:35]
	global_load_dword v156, v[64:65], off
	global_load_dword v158, v[64:65], off offset:4
	global_load_dword v160, v[64:65], off offset:8
	global_load_dword v162, v[64:65], off offset:12
	global_load_dword v164, v[64:65], off offset:32
	global_load_dword v166, v[64:65], off offset:36
	global_load_dword v168, v[64:65], off offset:40
	global_load_dword v170, v[64:65], off offset:44
	global_load_dword v172, v[64:65], off offset:64
	global_load_dword v174, v[64:65], off offset:68
	global_load_dword v176, v[64:65], off offset:72
	global_load_dword v196, v[64:65], off offset:76
	global_load_dword v198, v[64:65], off offset:96
	global_load_dword v200, v[64:65], off offset:100
	global_load_dword v202, v[64:65], off offset:104
	global_load_dword v204, v[64:65], off offset:108
	v_add_u32_e32 v130, s6, v1
	v_and_b32_e32 v60, 0x1e4, v130
	s_waitcnt lgkmcnt(1)
	v_mfma_f32_32x32x16_bf16 v[2:17], v[30:33], v[2:5], 0
	s_add_i32 s9, s5, s6
	s_cmpk_gt_u32 s9, 0x1ff
	s_cselect_b64 s[18:19], -1, 0
	s_waitcnt lgkmcnt(0)
	v_mfma_f32_32x32x16_bf16 v[2:17], v[22:25], v[18:21], v[2:17]
	ds_read_b128 v[26:29], v154 offset:64
	ds_read_b128 v[18:21], v153 offset:64
	s_waitcnt lgkmcnt(0)
	v_mfma_f32_32x32x16_bf16 v[2:17], v[26:29], v[18:21], v[2:17]
	ds_read_b128 v[18:21], v154 offset:96
	ds_read_b128 v[56:59], v153 offset:96
	s_waitcnt lgkmcnt(0)
	v_mfma_f32_32x32x16_bf16 v[2:17], v[18:21], v[56:59], v[2:17]
	v_cvt_f32_u32_e32 v56, v60
	v_div_scale_f32 v57, s[36:37], s52, s52, v56
	v_rcp_f32_e32 v58, v57
	s_mov_b64 s[36:37], -1
	v_fma_f32 v59, -v57, v58, 1.0
	v_fmac_f32_e32 v58, v59, v58
	v_div_scale_f32 v59, vcc, v56, s52, v56
	v_mul_f32_e32 v61, v59, v58
	v_fma_f32 v62, -v57, v61, v59
	v_fmac_f32_e32 v61, v62, v58
	v_fma_f32 v57, -v57, v61, v59
	v_div_fmas_f32 v57, v57, v58, v61
	v_div_fixup_f32 v56, v57, s52, v56
	v_fmamk_f32 v155, v56, 0x41447cbd, v217
	v_mul_f32_e64 v56, v71, |v155|
	v_mul_f32_e32 v56, 0x3fb8aa3b, v56
	v_exp_f32_e32 v56, v56
	v_mov_b32_e32 v57, v0
	s_and_b64 vcc, exec, s[18:19]
	s_waitcnt vmcnt(0)
	v_add_f32_e32 v2, v2, v156
	v_mul_f32_e32 v2, v56, v2
	v_mul_u32_u24_e32 v56, s7, v60
	v_lshlrev_b32_e32 v56, 1, v56
	v_lshl_add_u64 v[58:59], s[78:79], 0, v[56:57]
	v_lshl_add_u64 v[56:57], v[58:59], 0, s[76:77]
	s_cbranch_vccz .LBB0_454
	s_and_saveexec_b64 s[36:37], s[22:23]
	s_cbranch_execz .LBB0_453
	v_bfe_u32 v61, v2, 16, 1
	v_add3_u32 v61, v2, v61, s46
	v_lshlrev_b64 v[62:63], 1, v[50:51]
	v_lshrrev_b32_e32 v61, 16, v61
	v_lshl_add_u64 v[74:75], v[58:59], 0, v[62:63]
	v_lshl_add_u64 v[62:63], v[56:57], 0, v[62:63]
	global_store_short v[74:75], v61, off offset:16
	global_store_short v[62:63], v61, off offset:18

; __device__ __forceinline__ u16 f2bf(float f) { unsigned u = __float_as_uint(f); u += 0x7FFFu + ((u >> 16) & 1u); return (u16)(u >> 16); }
; __device__ __forceinline__ void phase_filter(const Params& p, int l, LAS unsigned char* lds, int bid, int G, int tid) {
;     ...
;                 for (int v = 0; v < 16; ++v) {
;                     const int ch = slab * 128 + ct * 32 + 8 * (v >> 2) + 4 * lh + (v & 3), cc = ch & 511;
;                     const float delta = fabsf(min_d + (max_d - min_d) * ((float)cc / 511.0f));
;                     float val = (acc[v] + b3[ch]) * __expf(-tt * delta);
;                     u16* kE = kbase + (size_t)cc * pitch; u16* kO = kE + (size_t)512 * pitch;
;                     if (ch < 512) { if (pos == 0) val += hd[cc]; const u16 b = f2bf(val); kE[8 + L - pos] = b; kO[9 + L - pos] = b;
;                         if (pos == L - 1) { kE[8] = 0; kO[9] = 0; }
;                         if (pos < 8) { kE[pos] = 0; kE[2 * L + 8 + pos] = 0; kO[pos] = 0; kO[2 * L + 9 + (pos < 7 ? pos : 0)] = 0; if (pos == 0) kO[8] = 0; } }
.LBB0_461:
	v_add_u32_e32 v2, 1, v130
	v_and_b32_e32 v2, 0x1e5, v2
	v_cvt_f32_u32_e32 v60, v2
	s_mov_b64 s[40:41], -1
	v_div_scale_f32 v61, s[36:37], s52, s52, v60
	v_rcp_f32_e32 v62, v61
	v_add_f32_e32 v3, v3, v158
	v_fma_f32 v63, -v61, v62, 1.0
	v_fmac_f32_e32 v62, v63, v62
	v_div_scale_f32 v63, vcc, v60, s52, v60
	v_mul_f32_e32 v74, v63, v62
	v_fma_f32 v75, -v61, v74, v63
	v_fmac_f32_e32 v74, v75, v62
	v_fma_f32 v61, -v61, v74, v63
	v_div_fmas_f32 v61, v61, v62, v74
	v_div_fixup_f32 v60, v61, s52, v60
	v_fmamk_f32 v157, v60, 0x41447cbd, v217
	v_mul_f32_e64 v60, v71, |v157|
	v_mul_f32_e32 v60, 0x3fb8aa3b, v60
	v_exp_f32_e32 v60, v60
	v_mov_b32_e32 v61, v0
	v_cndmask_b32_e64 v74, 0, 1, s[18:19]
	v_cmp_ne_u32_e64 s[36:37], 1, v74
	v_mul_f32_e32 v3, v60, v3
	v_mul_u32_u24_e32 v60, s7, v2
	v_lshlrev_b32_e32 v60, 1, v60
	v_lshl_add_u64 v[62:63], s[78:79], 0, v[60:61]
	v_lshl_add_u64 v[60:61], v[62:63], 0, s[76:77]
	s_andn2_b64 vcc, exec, s[18:19]
	s_cbranch_vccnz .LBB0_465
	s_and_saveexec_b64 s[18:19], s[22:23]
	s_cbranch_execz .LBB0_464
	v_bfe_u32 v74, v3, 16, 1
	v_add3_u32 v74, v3, v74, s46
	v_lshrrev_b32_e32 v78, 16, v74
	v_lshlrev_b64 v[74:75], 1, v[50:51]
	v_lshl_add_u64 v[76:77], v[62:63], 0, v[74:75]
	v_lshl_add_u64 v[74:75], v[60:61], 0, v[74:75]
	global_store_short v[76:77], v78, off offset:16
	global_store_short v[74:75], v78, off offset:18

; __device__ __forceinline__ u16 f2bf(float f) { unsigned u = __float_as_uint(f); u += 0x7FFFu + ((u >> 16) & 1u); return (u16)(u >> 16); }
; __device__ __forceinline__ void phase_filter(const Params& p, int l, LAS unsigned char* lds, int bid, int G, int tid) {
;     ...
;                 for (int v = 0; v < 16; ++v) {
;                     const int ch = slab * 128 + ct * 32 + 8 * (v >> 2) + 4 * lh + (v & 3), cc = ch & 511;
;                     const float delta = fabsf(min_d + (max_d - min_d) * ((float)cc / 511.0f));
;                     float val = (acc[v] + b3[ch]) * __expf(-tt * delta);
;                     u16* kE = kbase + (size_t)cc * pitch; u16* kO = kE + (size_t)512 * pitch;
;                     if (ch < 512) { if (pos == 0) val += hd[cc]; const u16 b = f2bf(val); kE[8 + L - pos] = b; kO[9 + L - pos] = b;
;                         if (pos == L - 1) { kE[8] = 0; kO[9] = 0; }
;                         if (pos < 8) { kE[pos] = 0; kE[2 * L + 8 + pos] = 0; kO[pos] = 0; kO[2 * L + 9 + (pos < 7 ? pos : 0)] = 0; if (pos == 0) kO[8] = 0; } }
.LBB0_472:
	v_add_u32_e32 v2, 2, v130
	v_and_b32_e32 v2, 0x1e6, v2
	v_cvt_f32_u32_e32 v3, v2
	v_div_scale_f32 v74, s[18:19], s52, s52, v3
	v_rcp_f32_e32 v75, v74
	s_mov_b64 s[18:19], -1
	v_fma_f32 v76, -v74, v75, 1.0
	v_fmac_f32_e32 v75, v76, v75
	v_div_scale_f32 v76, vcc, v3, s52, v3
	v_mul_f32_e32 v77, v76, v75
	v_fma_f32 v78, -v74, v77, v76
	v_fmac_f32_e32 v77, v78, v75
	v_fma_f32 v74, -v74, v77, v76
	v_div_fmas_f32 v74, v74, v75, v77
	v_div_fixup_f32 v3, v74, s52, v3
	v_fmamk_f32 v159, v3, 0x41447cbd, v217
	v_mov_b32_e32 v75, v0
	s_and_b64 vcc, exec, s[36:37]
	v_add_f32_e32 v3, v4, v160
	v_mul_f32_e64 v4, v71, |v159|
	v_mul_f32_e32 v4, 0x3fb8aa3b, v4
	v_exp_f32_e32 v4, v4
	s_nop 0
	v_mul_f32_e32 v3, v4, v3
	v_mul_u32_u24_e32 v4, s7, v2
	v_lshlrev_b32_e32 v74, 1, v4
	v_lshl_add_u64 v[74:75], s[78:79], 0, v[74:75]
	v_lshl_add_u64 v[76:77], v[74:75], 0, s[76:77]
	s_cbranch_vccnz .LBB0_476
	s_and_saveexec_b64 s[18:19], s[22:23]
	s_cbranch_execz .LBB0_475
	v_bfe_u32 v4, v3, 16, 1
	v_add3_u32 v4, v3, v4, s46
	v_lshlrev_b64 v[78:79], 1, v[50:51]
	v_lshrrev_b32_e32 v4, 16, v4
	v_lshl_add_u64 v[80:81], v[74:75], 0, v[78:79]
	v_lshl_add_u64 v[78:79], v[76:77], 0, v[78:79]
	global_store_short v[80:81], v4, off offset:16
	global_store_short v[78:79], v4, off offset:18

; __device__ __forceinline__ u16 f2bf(float f) { unsigned u = __float_as_uint(f); u += 0x7FFFu + ((u >> 16) & 1u); return (u16)(u >> 16); }
; __device__ __forceinline__ void phase_filter(const Params& p, int l, LAS unsigned char* lds, int bid, int G, int tid) {
;     ...
;                 for (int v = 0; v < 16; ++v) {
;                     const int ch = slab * 128 + ct * 32 + 8 * (v >> 2) + 4 * lh + (v & 3), cc = ch & 511;
;                     const float delta = fabsf(min_d + (max_d - min_d) * ((float)cc / 511.0f));
;                     float val = (acc[v] + b3[ch]) * __expf(-tt * delta);
;                     u16* kE = kbase + (size_t)cc * pitch; u16* kO = kE + (size_t)512 * pitch;
;                     if (ch < 512) { if (pos == 0) val += hd[cc]; const u16 b = f2bf(val); kE[8 + L - pos] = b; kO[9 + L - pos] = b;
;                         if (pos == L - 1) { kE[8] = 0; kO[9] = 0; }
;                         if (pos < 8) { kE[pos] = 0; kE[2 * L + 8 + pos] = 0; kO[pos] = 0; kO[2 * L + 9 + (pos < 7 ? pos : 0)] = 0; if (pos == 0) kO[8] = 0; } }
.LBB0_483:
	v_add_u32_e32 v2, 3, v130
	v_and_b32_e32 v2, 0x1e7, v2
	v_cvt_f32_u32_e32 v3, v2
	v_div_scale_f32 v4, s[18:19], s52, s52, v3
	v_rcp_f32_e32 v78, v4
	s_mov_b64 s[18:19], -1
	v_fma_f32 v79, -v4, v78, 1.0
	v_fmac_f32_e32 v78, v79, v78
	v_div_scale_f32 v79, vcc, v3, s52, v3
	v_mul_f32_e32 v80, v79, v78
	v_fma_f32 v81, -v4, v80, v79
	v_fmac_f32_e32 v80, v81, v78
	v_fma_f32 v4, -v4, v80, v79
	v_div_fmas_f32 v4, v4, v78, v80
	v_div_fixup_f32 v3, v4, s52, v3
	v_fmamk_f32 v161, v3, 0x41447cbd, v217
	v_mul_f32_e64 v4, v71, |v161|
	v_mul_f32_e32 v4, 0x3fb8aa3b, v4
	v_exp_f32_e32 v4, v4
	s_and_b64 vcc, exec, s[36:37]
	v_add_f32_e32 v3, v5, v162
	v_mul_f32_e32 v3, v4, v3
	v_mul_u32_u24_e32 v4, s7, v2
	v_lshlrev_b32_e32 v4, 1, v4
	v_mov_b32_e32 v5, v0
	v_lshl_add_u64 v[78:79], s[78:79], 0, v[4:5]
	v_lshl_add_u64 v[80:81], v[78:79], 0, s[76:77]
	s_cbranch_vccnz .LBB0_487
	s_and_saveexec_b64 s[18:19], s[22:23]
	s_cbranch_execz .LBB0_486
	v_bfe_u32 v4, v3, 16, 1
	v_add3_u32 v4, v3, v4, s46
	v_lshrrev_b32_e32 v84, 16, v4
	v_lshlrev_b64 v[4:5], 1, v[50:51]
	v_lshl_add_u64 v[82:83], v[78:79], 0, v[4:5]
	v_lshl_add_u64 v[4:5], v[80:81], 0, v[4:5]
	global_store_short v[82:83], v84, off offset:16
	global_store_short v[4:5], v84, off offset:18

; __device__ __forceinline__ u16 f2bf(float f) { unsigned u = __float_as_uint(f); u += 0x7FFFu + ((u >> 16) & 1u); return (u16)(u >> 16); }
; __device__ __forceinline__ void phase_filter(const Params& p, int l, LAS unsigned char* lds, int bid, int G, int tid) {
;     ...
;                 for (int v = 0; v < 16; ++v) {
;                     const int ch = slab * 128 + ct * 32 + 8 * (v >> 2) + 4 * lh + (v & 3), cc = ch & 511;
;                     const float delta = fabsf(min_d + (max_d - min_d) * ((float)cc / 511.0f));
;                     float val = (acc[v] + b3[ch]) * __expf(-tt * delta);
;                     u16* kE = kbase + (size_t)cc * pitch; u16* kO = kE + (size_t)512 * pitch;
;                     if (ch < 512) { if (pos == 0) val += hd[cc]; const u16 b = f2bf(val); kE[8 + L - pos] = b; kO[9 + L - pos] = b;
;                         if (pos == L - 1) { kE[8] = 0; kO[9] = 0; }
;                         if (pos < 8) { kE[pos] = 0; kE[2 * L + 8 + pos] = 0; kO[pos] = 0; kO[2 * L + 9 + (pos < 7 ? pos : 0)] = 0; if (pos == 0) kO[8] = 0; } }
.LBB0_494:
	v_add_u32_e32 v2, 8, v130
	v_and_b32_e32 v2, 0x1ec, v2
	v_cvt_f32_u32_e32 v3, v2
	v_div_scale_f32 v4, s[18:19], s52, s52, v3
	v_rcp_f32_e32 v5, v4
	s_mov_b64 s[18:19], -1
	v_fma_f32 v82, -v4, v5, 1.0
	v_fmac_f32_e32 v5, v82, v5
	v_div_scale_f32 v82, vcc, v3, s52, v3
	v_mul_f32_e32 v83, v82, v5
	v_fma_f32 v84, -v4, v83, v82
	v_fmac_f32_e32 v83, v84, v5
	v_fma_f32 v4, -v4, v83, v82
	v_div_fmas_f32 v4, v4, v5, v83
	v_div_fixup_f32 v3, v4, s52, v3
	v_fmamk_f32 v163, v3, 0x41447cbd, v217
	v_mul_f32_e64 v4, v71, |v163|
	v_mul_f32_e32 v4, 0x3fb8aa3b, v4
	v_exp_f32_e32 v4, v4
	v_mov_b32_e32 v5, v0
	s_and_b64 vcc, exec, s[36:37]
	v_add_f32_e32 v3, v6, v164
	v_mul_f32_e32 v3, v4, v3
	v_mul_u32_u24_e32 v4, s7, v2
	v_lshlrev_b32_e32 v4, 1, v4
	v_lshl_add_u64 v[82:83], s[78:79], 0, v[4:5]
	v_lshl_add_u64 v[84:85], v[82:83], 0, s[76:77]
	s_cbranch_vccnz .LBB0_498
	s_and_saveexec_b64 s[18:19], s[22:23]
	s_cbranch_execz .LBB0_497
	v_bfe_u32 v4, v3, 16, 1
	v_add3_u32 v4, v3, v4, s46
	v_lshrrev_b32_e32 v6, 16, v4
	v_lshlrev_b64 v[4:5], 1, v[50:51]
	v_lshl_add_u64 v[86:87], v[82:83], 0, v[4:5]
	v_lshl_add_u64 v[4:5], v[84:85], 0, v[4:5]
	global_store_short v[86:87], v6, off offset:16
	global_store_short v[4:5], v6, off offset:18

; __device__ __forceinline__ u16 f2bf(float f) { unsigned u = __float_as_uint(f); u += 0x7FFFu + ((u >> 16) & 1u); return (u16)(u >> 16); }
; __device__ __forceinline__ void phase_filter(const Params& p, int l, LAS unsigned char* lds, int bid, int G, int tid) {
;     ...
;                 for (int v = 0; v < 16; ++v) {
;                     const int ch = slab * 128 + ct * 32 + 8 * (v >> 2) + 4 * lh + (v & 3), cc = ch & 511;
;                     const float delta = fabsf(min_d + (max_d - min_d) * ((float)cc / 511.0f));
;                     float val = (acc[v] + b3[ch]) * __expf(-tt * delta);
;                     u16* kE = kbase + (size_t)cc * pitch; u16* kO = kE + (size_t)512 * pitch;
;                     if (ch < 512) { if (pos == 0) val += hd[cc]; const u16 b = f2bf(val); kE[8 + L - pos] = b; kO[9 + L - pos] = b;
;                         if (pos == L - 1) { kE[8] = 0; kO[9] = 0; }
;                         if (pos < 8) { kE[pos] = 0; kE[2 * L + 8 + pos] = 0; kO[pos] = 0; kO[2 * L + 9 + (pos < 7 ? pos : 0)] = 0; if (pos == 0) kO[8] = 0; } }
.LBB0_505:
	v_add_u32_e32 v2, 9, v130
	v_and_b32_e32 v2, 0x1ed, v2
	v_cvt_f32_u32_e32 v3, v2
	v_div_scale_f32 v4, s[18:19], s52, s52, v3
	v_rcp_f32_e32 v5, v4
	s_mov_b64 s[18:19], -1
	v_fma_f32 v6, -v4, v5, 1.0
	v_fmac_f32_e32 v5, v6, v5
	v_div_scale_f32 v6, vcc, v3, s52, v3
	v_mul_f32_e32 v86, v6, v5
	v_fma_f32 v87, -v4, v86, v6
	v_fmac_f32_e32 v86, v87, v5
	v_fma_f32 v4, -v4, v86, v6
	v_div_fmas_f32 v4, v4, v5, v86
	v_div_fixup_f32 v3, v4, s52, v3
	v_fmamk_f32 v165, v3, 0x41447cbd, v217
	v_mul_f32_e64 v4, v71, |v165|
	v_mul_f32_e32 v4, 0x3fb8aa3b, v4
	v_exp_f32_e32 v4, v4
	v_mov_b32_e32 v5, v0
	s_and_b64 vcc, exec, s[36:37]
	v_add_f32_e32 v3, v7, v166
	v_mul_f32_e32 v3, v4, v3
	v_mul_u32_u24_e32 v4, s7, v2
	v_lshlrev_b32_e32 v4, 1, v4
	v_lshl_add_u64 v[86:87], s[78:79], 0, v[4:5]
	v_lshl_add_u64 v[88:89], v[86:87], 0, s[76:77]
	s_cbranch_vccnz .LBB0_509
	s_and_saveexec_b64 s[18:19], s[22:23]
	s_cbranch_execz .LBB0_508
	v_bfe_u32 v4, v3, 16, 1
	v_add3_u32 v4, v3, v4, s46
	v_lshrrev_b32_e32 v90, 16, v4
	v_lshlrev_b64 v[4:5], 1, v[50:51]
	v_lshl_add_u64 v[6:7], v[86:87], 0, v[4:5]
	v_lshl_add_u64 v[4:5], v[88:89], 0, v[4:5]
	global_store_short v[6:7], v90, off offset:16
	global_store_short v[4:5], v90, off offset:18

; __device__ __forceinline__ u16 f2bf(float f) { unsigned u = __float_as_uint(f); u += 0x7FFFu + ((u >> 16) & 1u); return (u16)(u >> 16); }
; __device__ __forceinline__ void phase_filter(const Params& p, int l, LAS unsigned char* lds, int bid, int G, int tid) {
;     ...
;                 for (int v = 0; v < 16; ++v) {
;                     const int ch = slab * 128 + ct * 32 + 8 * (v >> 2) + 4 * lh + (v & 3), cc = ch & 511;
;                     const float delta = fabsf(min_d + (max_d - min_d) * ((float)cc / 511.0f));
;                     float val = (acc[v] + b3[ch]) * __expf(-tt * delta);
;                     u16* kE = kbase + (size_t)cc * pitch; u16* kO = kE + (size_t)512 * pitch;
;                     if (ch < 512) { if (pos == 0) val += hd[cc]; const u16 b = f2bf(val); kE[8 + L - pos] = b; kO[9 + L - pos] = b;
;                         if (pos == L - 1) { kE[8] = 0; kO[9] = 0; }
;                         if (pos < 8) { kE[pos] = 0; kE[2 * L + 8 + pos] = 0; kO[pos] = 0; kO[2 * L + 9 + (pos < 7 ? pos : 0)] = 0; if (pos == 0) kO[8] = 0; } }
;                     else { if (pos >= 1) { const u16 b = f2bf(val); kE[8 + L + pos] = b; kO[9 + L + pos] = b; } }
.LBB0_516:
	v_add_u32_e32 v2, 10, v130
	v_and_b32_e32 v2, 0x1ee, v2
	v_cvt_f32_u32_e32 v3, v2
	v_div_scale_f32 v4, s[18:19], s52, s52, v3
	v_rcp_f32_e32 v5, v4
	s_mov_b64 s[18:19], -1
	v_fma_f32 v6, -v4, v5, 1.0
	v_fmac_f32_e32 v5, v6, v5
	v_div_scale_f32 v6, vcc, v3, s52, v3
	v_mul_f32_e32 v7, v6, v5
	v_fma_f32 v90, -v4, v7, v6
	v_fmac_f32_e32 v7, v90, v5
	v_fma_f32 v4, -v4, v7, v6
	v_div_fmas_f32 v4, v4, v5, v7
	v_div_fixup_f32 v3, v4, s52, v3
	v_fmamk_f32 v167, v3, 0x41447cbd, v217
	v_mul_f32_e64 v4, v71, |v167|
	v_mul_f32_e32 v4, 0x3fb8aa3b, v4
	v_exp_f32_e32 v4, v4
	v_mov_b32_e32 v5, v0
	s_and_b64 vcc, exec, s[36:37]
	v_add_f32_e32 v3, v8, v168
	v_mul_f32_e32 v3, v4, v3
	v_mul_u32_u24_e32 v4, s7, v2
	v_lshlrev_b32_e32 v4, 1, v4
	v_lshl_add_u64 v[90:91], s[78:79], 0, v[4:5]
	v_lshl_add_u64 v[92:93], v[90:91], 0, s[76:77]
	s_cbranch_vccnz .LBB0_520
	s_and_saveexec_b64 s[18:19], s[22:23]
	s_cbranch_execz .LBB0_519
	v_bfe_u32 v4, v3, 16, 1
	v_add3_u32 v4, v3, v4, s46
	v_lshrrev_b32_e32 v8, 16, v4
	v_lshlrev_b64 v[4:5], 1, v[50:51]
	v_lshl_add_u64 v[6:7], v[90:91], 0, v[4:5]
	v_lshl_add_u64 v[4:5], v[92:93], 0, v[4:5]
	global_store_short v[6:7], v8, off offset:16
	global_store_short v[4:5], v8, off offset:18

; __device__ __forceinline__ u16 f2bf(float f) { unsigned u = __float_as_uint(f); u += 0x7FFFu + ((u >> 16) & 1u); return (u16)(u >> 16); }
; __device__ __forceinline__ void phase_filter(const Params& p, int l, LAS unsigned char* lds, int bid, int G, int tid) {
;     ...
;                 for (int v = 0; v < 16; ++v) {
;                     const int ch = slab * 128 + ct * 32 + 8 * (v >> 2) + 4 * lh + (v & 3), cc = ch & 511;
;                     const float delta = fabsf(min_d + (max_d - min_d) * ((float)cc / 511.0f));
;                     float val = (acc[v] + b3[ch]) * __expf(-tt * delta);
;                     u16* kE = kbase + (size_t)cc * pitch; u16* kO = kE + (size_t)512 * pitch;
;                     if (ch < 512) { if (pos == 0) val += hd[cc]; const u16 b = f2bf(val); kE[8 + L - pos] = b; kO[9 + L - pos] = b;
;                         if (pos == L - 1) { kE[8] = 0; kO[9] = 0; }
;                         if (pos < 8) { kE[pos] = 0; kE[2 * L + 8 + pos] = 0; kO[pos] = 0; kO[2 * L + 9 + (pos < 7 ? pos : 0)] = 0; if (pos == 0) kO[8] = 0; } }
;                     else { if (pos >= 1) { const u16 b = f2bf(val); kE[8 + L + pos] = b; kO[9 + L + pos] = b; } }
.LBB0_527:
	v_add_u32_e32 v2, 11, v130
	v_and_b32_e32 v2, 0x1ef, v2
	v_cvt_f32_u32_e32 v3, v2
	v_div_scale_f32 v4, s[18:19], s52, s52, v3
	v_rcp_f32_e32 v5, v4
	s_mov_b64 s[18:19], -1
	v_fma_f32 v6, -v4, v5, 1.0
	v_fmac_f32_e32 v5, v6, v5
	v_div_scale_f32 v6, vcc, v3, s52, v3
	v_mul_f32_e32 v7, v6, v5
	v_fma_f32 v8, -v4, v7, v6
	v_fmac_f32_e32 v7, v8, v5
	v_fma_f32 v4, -v4, v7, v6
	v_div_fmas_f32 v4, v4, v5, v7
	v_div_fixup_f32 v3, v4, s52, v3
	v_fmamk_f32 v169, v3, 0x41447cbd, v217
	v_mul_f32_e64 v4, v71, |v169|
	v_mul_f32_e32 v4, 0x3fb8aa3b, v4
	v_exp_f32_e32 v4, v4
	v_mov_b32_e32 v5, v0
	s_and_b64 vcc, exec, s[36:37]
	v_add_f32_e32 v3, v9, v170
	v_mul_f32_e32 v3, v4, v3
	v_mul_u32_u24_e32 v4, s7, v2
	v_lshlrev_b32_e32 v4, 1, v4
	v_lshl_add_u64 v[94:95], s[78:79], 0, v[4:5]
	v_lshl_add_u64 v[96:97], v[94:95], 0, s[76:77]
	s_cbranch_vccnz .LBB0_531
	s_and_saveexec_b64 s[18:19], s[22:23]
	s_cbranch_execz .LBB0_530
	v_bfe_u32 v4, v3, 16, 1
	v_add3_u32 v4, v3, v4, s46
	v_lshrrev_b32_e32 v8, 16, v4
	v_lshlrev_b64 v[4:5], 1, v[50:51]
	v_lshl_add_u64 v[6:7], v[94:95], 0, v[4:5]
	v_lshl_add_u64 v[4:5], v[96:97], 0, v[4:5]
	global_store_short v[6:7], v8, off offset:16
	global_store_short v[4:5], v8, off offset:18

; __device__ __forceinline__ u16 f2bf(float f) { unsigned u = __float_as_uint(f); u += 0x7FFFu + ((u >> 16) & 1u); return (u16)(u >> 16); }
; __device__ __forceinline__ void phase_filter(const Params& p, int l, LAS unsigned char* lds, int bid, int G, int tid) {
;     ...
;                 for (int v = 0; v < 16; ++v) {
;                     const int ch = slab * 128 + ct * 32 + 8 * (v >> 2) + 4 * lh + (v & 3), cc = ch & 511;
;                     const float delta = fabsf(min_d + (max_d - min_d) * ((float)cc / 511.0f));
;                     float val = (acc[v] + b3[ch]) * __expf(-tt * delta);
;                     u16* kE = kbase + (size_t)cc * pitch; u16* kO = kE + (size_t)512 * pitch;
;                     if (ch < 512) { if (pos == 0) val += hd[cc]; const u16 b = f2bf(val); kE[8 + L - pos] = b; kO[9 + L - pos] = b;
;                         if (pos == L - 1) { kE[8] = 0; kO[9] = 0; }
;                         if (pos < 8) { kE[pos] = 0; kE[2 * L + 8 + pos] = 0; kO[pos] = 0; kO[2 * L + 9 + (pos < 7 ? pos : 0)] = 0; if (pos == 0) kO[8] = 0; } }
;                     else { if (pos >= 1) { const u16 b = f2bf(val); kE[8 + L + pos] = b; kO[9 + L + pos] = b; } }
.LBB0_538:
	v_add_u32_e32 v2, 16, v130
	v_and_b32_e32 v2, 0x1f4, v2
	v_cvt_f32_u32_e32 v3, v2
	v_div_scale_f32 v4, s[18:19], s52, s52, v3
	v_rcp_f32_e32 v5, v4
	s_mov_b64 s[18:19], -1
	v_fma_f32 v6, -v4, v5, 1.0
	v_fmac_f32_e32 v5, v6, v5
	v_div_scale_f32 v6, vcc, v3, s52, v3
	v_mul_f32_e32 v7, v6, v5
	v_fma_f32 v8, -v4, v7, v6
	v_fmac_f32_e32 v7, v8, v5
	v_fma_f32 v4, -v4, v7, v6
	v_div_fmas_f32 v4, v4, v5, v7
	v_div_fixup_f32 v3, v4, s52, v3
	v_fmamk_f32 v171, v3, 0x41447cbd, v217
	v_mul_f32_e64 v4, v71, |v171|
	v_mul_f32_e32 v4, 0x3fb8aa3b, v4
	v_exp_f32_e32 v4, v4
	v_mov_b32_e32 v5, v0
	s_and_b64 vcc, exec, s[36:37]
	v_add_f32_e32 v3, v10, v172
	v_mul_f32_e32 v3, v4, v3
	v_mul_u32_u24_e32 v4, s7, v2
	v_lshlrev_b32_e32 v4, 1, v4
	v_lshl_add_u64 v[102:103], s[78:79], 0, v[4:5]
	v_lshl_add_u64 v[104:105], v[102:103], 0, s[76:77]
	s_cbranch_vccnz .LBB0_542
	s_and_saveexec_b64 s[18:19], s[22:23]
	s_cbranch_execz .LBB0_541
	v_bfe_u32 v4, v3, 16, 1
	v_add3_u32 v4, v3, v4, s46
	v_lshrrev_b32_e32 v8, 16, v4
	v_lshlrev_b64 v[4:5], 1, v[50:51]
	v_lshl_add_u64 v[6:7], v[102:103], 0, v[4:5]
	v_lshl_add_u64 v[4:5], v[104:105], 0, v[4:5]
	global_store_short v[6:7], v8, off offset:16
	global_store_short v[4:5], v8, off offset:18

; __device__ __forceinline__ u16 f2bf(float f) { unsigned u = __float_as_uint(f); u += 0x7FFFu + ((u >> 16) & 1u); return (u16)(u >> 16); }
; __device__ __forceinline__ void phase_filter(const Params& p, int l, LAS unsigned char* lds, int bid, int G, int tid) {
;     ...
;                 for (int v = 0; v < 16; ++v) {
;                     const int ch = slab * 128 + ct * 32 + 8 * (v >> 2) + 4 * lh + (v & 3), cc = ch & 511;
;                     const float delta = fabsf(min_d + (max_d - min_d) * ((float)cc / 511.0f));
;                     float val = (acc[v] + b3[ch]) * __expf(-tt * delta);
;                     u16* kE = kbase + (size_t)cc * pitch; u16* kO = kE + (size_t)512 * pitch;
;                     if (ch < 512) { if (pos == 0) val += hd[cc]; const u16 b = f2bf(val); kE[8 + L - pos] = b; kO[9 + L - pos] = b;
;                         if (pos == L - 1) { kE[8] = 0; kO[9] = 0; }
;                         if (pos < 8) { kE[pos] = 0; kE[2 * L + 8 + pos] = 0; kO[pos] = 0; kO[2 * L + 9 + (pos < 7 ? pos : 0)] = 0; if (pos == 0) kO[8] = 0; } }
;                     else { if (pos >= 1) { const u16 b = f2bf(val); kE[8 + L + pos] = b; kO[9 + L + pos] = b; } }
.LBB0_549:
	v_add_u32_e32 v2, 17, v130
	v_and_b32_e32 v2, 0x1f5, v2
	v_cvt_f32_u32_e32 v3, v2
	v_div_scale_f32 v4, s[18:19], s52, s52, v3
	v_rcp_f32_e32 v5, v4
	s_mov_b64 s[18:19], -1
	v_fma_f32 v6, -v4, v5, 1.0
	v_fmac_f32_e32 v5, v6, v5
	v_div_scale_f32 v6, vcc, v3, s52, v3
	v_mul_f32_e32 v7, v6, v5
	v_fma_f32 v8, -v4, v7, v6
	v_fmac_f32_e32 v7, v8, v5
	v_fma_f32 v4, -v4, v7, v6
	v_div_fmas_f32 v4, v4, v5, v7
	v_div_fixup_f32 v3, v4, s52, v3
	v_fmamk_f32 v173, v3, 0x41447cbd, v217
	v_mul_f32_e64 v4, v71, |v173|
	v_mul_f32_e32 v4, 0x3fb8aa3b, v4
	v_exp_f32_e32 v4, v4
	v_mov_b32_e32 v5, v0
	s_and_b64 vcc, exec, s[36:37]
	v_add_f32_e32 v3, v11, v174
	v_mul_f32_e32 v3, v4, v3
	v_mul_u32_u24_e32 v4, s7, v2
	v_lshlrev_b32_e32 v4, 1, v4
	v_lshl_add_u64 v[106:107], s[78:79], 0, v[4:5]
	v_lshl_add_u64 v[108:109], v[106:107], 0, s[76:77]
	s_cbranch_vccnz .LBB0_553
	s_and_saveexec_b64 s[18:19], s[22:23]
	s_cbranch_execz .LBB0_552
	v_bfe_u32 v4, v3, 16, 1
	v_add3_u32 v4, v3, v4, s46
	v_lshrrev_b32_e32 v8, 16, v4
	v_lshlrev_b64 v[4:5], 1, v[50:51]
	v_lshl_add_u64 v[6:7], v[106:107], 0, v[4:5]
	v_lshl_add_u64 v[4:5], v[108:109], 0, v[4:5]
	global_store_short v[6:7], v8, off offset:16
	global_store_short v[4:5], v8, off offset:18

; __device__ __forceinline__ u16 f2bf(float f) { unsigned u = __float_as_uint(f); u += 0x7FFFu + ((u >> 16) & 1u); return (u16)(u >> 16); }
; __device__ __forceinline__ void phase_filter(const Params& p, int l, LAS unsigned char* lds, int bid, int G, int tid) {
;     ...
;                 for (int v = 0; v < 16; ++v) {
;                     const int ch = slab * 128 + ct * 32 + 8 * (v >> 2) + 4 * lh + (v & 3), cc = ch & 511;
;                     const float delta = fabsf(min_d + (max_d - min_d) * ((float)cc / 511.0f));
;                     float val = (acc[v] + b3[ch]) * __expf(-tt * delta);
;                     u16* kE = kbase + (size_t)cc * pitch; u16* kO = kE + (size_t)512 * pitch;
;                     if (ch < 512) { if (pos == 0) val += hd[cc]; const u16 b = f2bf(val); kE[8 + L - pos] = b; kO[9 + L - pos] = b;
;                         if (pos == L - 1) { kE[8] = 0; kO[9] = 0; }
;                         if (pos < 8) { kE[pos] = 0; kE[2 * L + 8 + pos] = 0; kO[pos] = 0; kO[2 * L + 9 + (pos < 7 ? pos : 0)] = 0; if (pos == 0) kO[8] = 0; } }
;                     else { if (pos >= 1) { const u16 b = f2bf(val); kE[8 + L + pos] = b; kO[9 + L + pos] = b; } }
.LBB0_560:
	v_add_u32_e32 v2, 18, v130
	v_and_b32_e32 v2, 0x1f6, v2
	v_cvt_f32_u32_e32 v3, v2
	v_div_scale_f32 v4, s[18:19], s52, s52, v3
	v_rcp_f32_e32 v5, v4
	s_mov_b64 s[18:19], -1
	v_fma_f32 v6, -v4, v5, 1.0
	v_fmac_f32_e32 v5, v6, v5
	v_div_scale_f32 v6, vcc, v3, s52, v3
	v_mul_f32_e32 v7, v6, v5
	v_fma_f32 v8, -v4, v7, v6
	v_fmac_f32_e32 v7, v8, v5
	v_fma_f32 v4, -v4, v7, v6
	v_div_fmas_f32 v4, v4, v5, v7
	v_div_fixup_f32 v3, v4, s52, v3
	v_fmamk_f32 v175, v3, 0x41447cbd, v217
	v_mul_f32_e64 v4, v71, |v175|
	v_mul_f32_e32 v4, 0x3fb8aa3b, v4
	v_exp_f32_e32 v4, v4
	v_mov_b32_e32 v5, v0
	s_and_b64 vcc, exec, s[36:37]
	v_add_f32_e32 v3, v12, v176
	v_mul_f32_e32 v3, v4, v3
	v_mul_u32_u24_e32 v4, s7, v2
	v_lshlrev_b32_e32 v4, 1, v4
	v_lshl_add_u64 v[110:111], s[78:79], 0, v[4:5]
	v_lshl_add_u64 v[112:113], v[110:111], 0, s[76:77]
	s_cbranch_vccnz .LBB0_564
	s_and_saveexec_b64 s[18:19], s[22:23]
	s_cbranch_execz .LBB0_563
	v_bfe_u32 v4, v3, 16, 1
	v_add3_u32 v4, v3, v4, s46
	v_lshrrev_b32_e32 v8, 16, v4
	v_lshlrev_b64 v[4:5], 1, v[50:51]
	v_lshl_add_u64 v[6:7], v[110:111], 0, v[4:5]
	v_lshl_add_u64 v[4:5], v[112:113], 0, v[4:5]
	global_store_short v[6:7], v8, off offset:16
	global_store_short v[4:5], v8, off offset:18

; __device__ __forceinline__ u16 f2bf(float f) { unsigned u = __float_as_uint(f); u += 0x7FFFu + ((u >> 16) & 1u); return (u16)(u >> 16); }
; __device__ __forceinline__ void phase_filter(const Params& p, int l, LAS unsigned char* lds, int bid, int G, int tid) {
;     ...
;                 for (int v = 0; v < 16; ++v) {
;                     const int ch = slab * 128 + ct * 32 + 8 * (v >> 2) + 4 * lh + (v & 3), cc = ch & 511;
;                     const float delta = fabsf(min_d + (max_d - min_d) * ((float)cc / 511.0f));
;                     float val = (acc[v] + b3[ch]) * __expf(-tt * delta);
;                     u16* kE = kbase + (size_t)cc * pitch; u16* kO = kE + (size_t)512 * pitch;
;                     if (ch < 512) { if (pos == 0) val += hd[cc]; const u16 b = f2bf(val); kE[8 + L - pos] = b; kO[9 + L - pos] = b;
;                         if (pos == L - 1) { kE[8] = 0; kO[9] = 0; }
;                         if (pos < 8) { kE[pos] = 0; kE[2 * L + 8 + pos] = 0; kO[pos] = 0; kO[2 * L + 9 + (pos < 7 ? pos : 0)] = 0; if (pos == 0) kO[8] = 0; } }
;                     else { if (pos >= 1) { const u16 b = f2bf(val); kE[8 + L + pos] = b; kO[9 + L + pos] = b; } }
.LBB0_571:
	v_add_u32_e32 v2, 19, v130
	v_and_b32_e32 v2, 0x1f7, v2
	v_cvt_f32_u32_e32 v3, v2
	v_div_scale_f32 v4, s[18:19], s52, s52, v3
	v_rcp_f32_e32 v5, v4
	s_mov_b64 s[18:19], -1
	v_fma_f32 v6, -v4, v5, 1.0
	v_fmac_f32_e32 v5, v6, v5
	v_div_scale_f32 v6, vcc, v3, s52, v3
	v_mul_f32_e32 v7, v6, v5
	v_fma_f32 v8, -v4, v7, v6
	v_fmac_f32_e32 v7, v8, v5
	v_fma_f32 v4, -v4, v7, v6
	v_div_fmas_f32 v4, v4, v5, v7
	v_div_fixup_f32 v3, v4, s52, v3
	v_fmamk_f32 v177, v3, 0x41447cbd, v217
	v_mul_f32_e64 v4, v71, |v177|
	v_mul_f32_e32 v4, 0x3fb8aa3b, v4
	v_exp_f32_e32 v4, v4
	v_mov_b32_e32 v5, v0
	s_and_b64 vcc, exec, s[36:37]
	v_add_f32_e32 v3, v13, v196
	v_mul_f32_e32 v3, v4, v3
	v_mul_u32_u24_e32 v4, s7, v2
	v_lshlrev_b32_e32 v4, 1, v4
	v_lshl_add_u64 v[114:115], s[78:79], 0, v[4:5]
	v_lshl_add_u64 v[116:117], v[114:115], 0, s[76:77]
	s_cbranch_vccnz .LBB0_575
	s_and_saveexec_b64 s[18:19], s[22:23]
	s_cbranch_execz .LBB0_574
	v_bfe_u32 v4, v3, 16, 1
	v_add3_u32 v4, v3, v4, s46
	v_lshrrev_b32_e32 v8, 16, v4
	v_lshlrev_b64 v[4:5], 1, v[50:51]
	v_lshl_add_u64 v[6:7], v[114:115], 0, v[4:5]
	v_lshl_add_u64 v[4:5], v[116:117], 0, v[4:5]
	global_store_short v[6:7], v8, off offset:16
	global_store_short v[4:5], v8, off offset:18

; __device__ __forceinline__ u16 f2bf(float f) { unsigned u = __float_as_uint(f); u += 0x7FFFu + ((u >> 16) & 1u); return (u16)(u >> 16); }
; __device__ __forceinline__ void phase_filter(const Params& p, int l, LAS unsigned char* lds, int bid, int G, int tid) {
;     ...
;                 for (int v = 0; v < 16; ++v) {
;                     const int ch = slab * 128 + ct * 32 + 8 * (v >> 2) + 4 * lh + (v & 3), cc = ch & 511;
;                     const float delta = fabsf(min_d + (max_d - min_d) * ((float)cc / 511.0f));
;                     float val = (acc[v] + b3[ch]) * __expf(-tt * delta);
;                     u16* kE = kbase + (size_t)cc * pitch; u16* kO = kE + (size_t)512 * pitch;
;                     if (ch < 512) { if (pos == 0) val += hd[cc]; const u16 b = f2bf(val); kE[8 + L - pos] = b; kO[9 + L - pos] = b;
;                         if (pos == L - 1) { kE[8] = 0; kO[9] = 0; }
;                         if (pos < 8) { kE[pos] = 0; kE[2 * L + 8 + pos] = 0; kO[pos] = 0; kO[2 * L + 9 + (pos < 7 ? pos : 0)] = 0; if (pos == 0) kO[8] = 0; } }
;                     else { if (pos >= 1) { const u16 b = f2bf(val); kE[8 + L + pos] = b; kO[9 + L + pos] = b; } }
.LBB0_582:
	v_add_u32_e32 v2, 24, v130
	v_and_b32_e32 v2, 0x1fc, v2
	v_cvt_f32_u32_e32 v3, v2
	v_div_scale_f32 v4, s[18:19], s52, s52, v3
	v_rcp_f32_e32 v5, v4
	s_mov_b64 s[18:19], -1
	v_fma_f32 v6, -v4, v5, 1.0
	v_fmac_f32_e32 v5, v6, v5
	v_div_scale_f32 v6, vcc, v3, s52, v3
	v_mul_f32_e32 v7, v6, v5
	v_fma_f32 v8, -v4, v7, v6
	v_fmac_f32_e32 v7, v8, v5
	v_fma_f32 v4, -v4, v7, v6
	v_div_fmas_f32 v4, v4, v5, v7
	v_div_fixup_f32 v3, v4, s52, v3
	v_fmamk_f32 v197, v3, 0x41447cbd, v217
	v_mul_f32_e64 v4, v71, |v197|
	v_mul_f32_e32 v4, 0x3fb8aa3b, v4
	v_exp_f32_e32 v4, v4
	v_mov_b32_e32 v5, v0
	s_and_b64 vcc, exec, s[36:37]
	v_add_f32_e32 v3, v14, v198
	v_mul_f32_e32 v3, v4, v3
	v_mul_u32_u24_e32 v4, s7, v2
	v_lshlrev_b32_e32 v4, 1, v4
	v_lshl_add_u64 v[118:119], s[78:79], 0, v[4:5]
	v_lshl_add_u64 v[120:121], v[118:119], 0, s[76:77]
	s_cbranch_vccnz .LBB0_586
	s_and_saveexec_b64 s[18:19], s[22:23]
	s_cbranch_execz .LBB0_585
	v_bfe_u32 v4, v3, 16, 1
	v_add3_u32 v4, v3, v4, s46
	v_lshrrev_b32_e32 v8, 16, v4
	v_lshlrev_b64 v[4:5], 1, v[50:51]
	v_lshl_add_u64 v[6:7], v[118:119], 0, v[4:5]
	v_lshl_add_u64 v[4:5], v[120:121], 0, v[4:5]
	global_store_short v[6:7], v8, off offset:16
	global_store_short v[4:5], v8, off offset:18

; __device__ __forceinline__ u16 f2bf(float f) { unsigned u = __float_as_uint(f); u += 0x7FFFu + ((u >> 16) & 1u); return (u16)(u >> 16); }
; __device__ __forceinline__ void phase_filter(const Params& p, int l, LAS unsigned char* lds, int bid, int G, int tid) {
;     ...
;                 for (int v = 0; v < 16; ++v) {
;                     const int ch = slab * 128 + ct * 32 + 8 * (v >> 2) + 4 * lh + (v & 3), cc = ch & 511;
;                     const float delta = fabsf(min_d + (max_d - min_d) * ((float)cc / 511.0f));
;                     float val = (acc[v] + b3[ch]) * __expf(-tt * delta);
;                     u16* kE = kbase + (size_t)cc * pitch; u16* kO = kE + (size_t)512 * pitch;
;                     if (ch < 512) { if (pos == 0) val += hd[cc]; const u16 b = f2bf(val); kE[8 + L - pos] = b; kO[9 + L - pos] = b;
;                         if (pos == L - 1) { kE[8] = 0; kO[9] = 0; }
;                         if (pos < 8) { kE[pos] = 0; kE[2 * L + 8 + pos] = 0; kO[pos] = 0; kO[2 * L + 9 + (pos < 7 ? pos : 0)] = 0; if (pos == 0) kO[8] = 0; } }
;                     else { if (pos >= 1) { const u16 b = f2bf(val); kE[8 + L + pos] = b; kO[9 + L + pos] = b; } }
.LBB0_593:
	v_add_u32_e32 v2, 25, v130
	v_and_b32_e32 v2, 0x1fd, v2
	v_cvt_f32_u32_e32 v3, v2
	v_div_scale_f32 v4, s[18:19], s52, s52, v3
	v_rcp_f32_e32 v5, v4
	s_mov_b64 s[18:19], -1
	v_fma_f32 v6, -v4, v5, 1.0
	v_fmac_f32_e32 v5, v6, v5
	v_div_scale_f32 v6, vcc, v3, s52, v3
	v_mul_f32_e32 v7, v6, v5
	v_fma_f32 v8, -v4, v7, v6
	v_fmac_f32_e32 v7, v8, v5
	v_fma_f32 v4, -v4, v7, v6
	v_div_fmas_f32 v4, v4, v5, v7
	v_div_fixup_f32 v3, v4, s52, v3
	v_fmamk_f32 v199, v3, 0x41447cbd, v217
	v_mul_f32_e64 v4, v71, |v199|
	v_mul_f32_e32 v4, 0x3fb8aa3b, v4
	v_exp_f32_e32 v4, v4
	v_mov_b32_e32 v5, v0
	s_and_b64 vcc, exec, s[36:37]
	v_add_f32_e32 v3, v15, v200
	v_mul_f32_e32 v3, v4, v3
	v_mul_u32_u24_e32 v4, s7, v2
	v_lshlrev_b32_e32 v4, 1, v4
	v_lshl_add_u64 v[122:123], s[78:79], 0, v[4:5]
	v_lshl_add_u64 v[124:125], v[122:123], 0, s[76:77]
	s_cbranch_vccnz .LBB0_597
	s_and_saveexec_b64 s[18:19], s[22:23]
	s_cbranch_execz .LBB0_596
	v_bfe_u32 v4, v3, 16, 1
	v_add3_u32 v4, v3, v4, s46
	v_lshrrev_b32_e32 v8, 16, v4
	v_lshlrev_b64 v[4:5], 1, v[50:51]
	v_lshl_add_u64 v[6:7], v[122:123], 0, v[4:5]
	v_lshl_add_u64 v[4:5], v[124:125], 0, v[4:5]
	global_store_short v[6:7], v8, off offset:16
	global_store_short v[4:5], v8, off offset:18

; __device__ __forceinline__ u16 f2bf(float f) { unsigned u = __float_as_uint(f); u += 0x7FFFu + ((u >> 16) & 1u); return (u16)(u >> 16); }
; __device__ __forceinline__ void phase_filter(const Params& p, int l, LAS unsigned char* lds, int bid, int G, int tid) {
;     ...
;                 for (int v = 0; v < 16; ++v) {
;                     const int ch = slab * 128 + ct * 32 + 8 * (v >> 2) + 4 * lh + (v & 3), cc = ch & 511;
;                     const float delta = fabsf(min_d + (max_d - min_d) * ((float)cc / 511.0f));
;                     float val = (acc[v] + b3[ch]) * __expf(-tt * delta);
;                     u16* kE = kbase + (size_t)cc * pitch; u16* kO = kE + (size_t)512 * pitch;
;                     if (ch < 512) { if (pos == 0) val += hd[cc]; const u16 b = f2bf(val); kE[8 + L - pos] = b; kO[9 + L - pos] = b;
;                         if (pos == L - 1) { kE[8] = 0; kO[9] = 0; }
;                         if (pos < 8) { kE[pos] = 0; kE[2 * L + 8 + pos] = 0; kO[pos] = 0; kO[2 * L + 9 + (pos < 7 ? pos : 0)] = 0; if (pos == 0) kO[8] = 0; } }
;                     else { if (pos >= 1) { const u16 b = f2bf(val); kE[8 + L + pos] = b; kO[9 + L + pos] = b; } }
.LBB0_604:
	v_add_u32_e32 v2, 26, v130
	v_and_b32_e32 v2, 0x1fe, v2
	v_cvt_f32_u32_e32 v3, v2
	v_div_scale_f32 v4, s[18:19], s52, s52, v3
	v_rcp_f32_e32 v5, v4
	s_mov_b64 s[18:19], -1
	v_fma_f32 v6, -v4, v5, 1.0
	v_fmac_f32_e32 v5, v6, v5
	v_div_scale_f32 v6, vcc, v3, s52, v3
	v_mul_f32_e32 v7, v6, v5
	v_fma_f32 v8, -v4, v7, v6
	v_fmac_f32_e32 v7, v8, v5
	v_fma_f32 v4, -v4, v7, v6
	v_div_fmas_f32 v4, v4, v5, v7
	v_div_fixup_f32 v3, v4, s52, v3
	v_fmamk_f32 v201, v3, 0x41447cbd, v217
	v_mul_f32_e64 v4, v71, |v201|
	v_mul_f32_e32 v4, 0x3fb8aa3b, v4
	v_exp_f32_e32 v4, v4
	v_mov_b32_e32 v5, v0
	s_and_b64 vcc, exec, s[36:37]
	v_add_f32_e32 v3, v16, v202
	v_mul_f32_e32 v3, v4, v3
	v_mul_u32_u24_e32 v4, s7, v2
	v_lshlrev_b32_e32 v4, 1, v4
	v_lshl_add_u64 v[126:127], s[78:79], 0, v[4:5]
	v_lshl_add_u64 v[128:129], v[126:127], 0, s[76:77]
	s_cbranch_vccnz .LBB0_608
	s_and_saveexec_b64 s[18:19], s[22:23]
	s_cbranch_execz .LBB0_607
	v_bfe_u32 v4, v3, 16, 1
	v_add3_u32 v4, v3, v4, s46
	v_lshrrev_b32_e32 v8, 16, v4
	v_lshlrev_b64 v[4:5], 1, v[50:51]
	v_lshl_add_u64 v[6:7], v[126:127], 0, v[4:5]
	v_lshl_add_u64 v[4:5], v[128:129], 0, v[4:5]
	global_store_short v[6:7], v8, off offset:16
	global_store_short v[4:5], v8, off offset:18

; __device__ __forceinline__ u16 f2bf(float f) { unsigned u = __float_as_uint(f); u += 0x7FFFu + ((u >> 16) & 1u); return (u16)(u >> 16); }
; __device__ __forceinline__ void phase_filter(const Params& p, int l, LAS unsigned char* lds, int bid, int G, int tid) {
;     ...
;                 for (int v = 0; v < 16; ++v) {
;                     const int ch = slab * 128 + ct * 32 + 8 * (v >> 2) + 4 * lh + (v & 3), cc = ch & 511;
;                     const float delta = fabsf(min_d + (max_d - min_d) * ((float)cc / 511.0f));
;                     float val = (acc[v] + b3[ch]) * __expf(-tt * delta);
;                     u16* kE = kbase + (size_t)cc * pitch; u16* kO = kE + (size_t)512 * pitch;
;                     if (ch < 512) { if (pos == 0) val += hd[cc]; const u16 b = f2bf(val); kE[8 + L - pos] = b; kO[9 + L - pos] = b;
;                         if (pos == L - 1) { kE[8] = 0; kO[9] = 0; }
;                         if (pos < 8) { kE[pos] = 0; kE[2 * L + 8 + pos] = 0; kO[pos] = 0; kO[2 * L + 9 + (pos < 7 ? pos : 0)] = 0; if (pos == 0) kO[8] = 0; } }
;                     else { if (pos >= 1) { const u16 b = f2bf(val); kE[8 + L + pos] = b; kO[9 + L + pos] = b; } }
.LBB0_615:
	v_add_u32_e32 v2, 27, v130
	v_and_b32_e32 v2, 0x1ff, v2
	v_cvt_f32_u32_e32 v3, v2
	v_div_scale_f32 v4, s[18:19], s52, s52, v3
	v_rcp_f32_e32 v5, v4
	s_mov_b64 s[18:19], -1
	v_fma_f32 v6, -v4, v5, 1.0
	v_fmac_f32_e32 v5, v6, v5
	v_div_scale_f32 v6, vcc, v3, s52, v3
	v_mul_f32_e32 v7, v6, v5
	v_fma_f32 v8, -v4, v7, v6
	v_fmac_f32_e32 v7, v8, v5
	v_fma_f32 v4, -v4, v7, v6
	v_div_fmas_f32 v4, v4, v5, v7
	v_div_fixup_f32 v3, v4, s52, v3
	v_fmamk_f32 v203, v3, 0x41447cbd, v217
	v_mul_f32_e64 v4, v71, |v203|
	v_mul_f32_e32 v4, 0x3fb8aa3b, v4
	v_exp_f32_e32 v4, v4
	v_mov_b32_e32 v5, v0
	s_and_b64 vcc, exec, s[36:37]
	v_add_f32_e32 v3, v17, v204
	v_mul_f32_e32 v3, v4, v3
	v_mul_u32_u24_e32 v4, s7, v2
	v_lshlrev_b32_e32 v4, 1, v4
	v_lshl_add_u64 v[64:65], s[78:79], 0, v[4:5]
	v_lshl_add_u64 v[130:131], v[64:65], 0, s[76:77]
	s_cbranch_vccnz .LBB0_619
	s_and_saveexec_b64 s[18:19], s[22:23]
	s_cbranch_execz .LBB0_618
	v_bfe_u32 v4, v3, 16, 1
	v_add3_u32 v4, v3, v4, s46
	v_lshrrev_b32_e32 v8, 16, v4
	v_lshlrev_b64 v[4:5], 1, v[50:51]
	v_lshl_add_u64 v[6:7], v[64:65], 0, v[4:5]
	v_lshl_add_u64 v[4:5], v[130:131], 0, v[4:5]
	global_store_short v[6:7], v8, off offset:16
	global_store_short v[4:5], v8, off offset:18
